# v14 + scan: two of the three cumulative-decay barriers removed (stage-0 exchange is wave-local; per-wave prefix row makes the cum read wave-local)
# speedup vs baseline: 1.0167x; 1.0021x over previous
.LBB0_522:
	v_readlane_b32 s0, v255, 29
	s_add_i32 s3, s0, 3
	s_cmp_ge_i32 s3, s72
	s_cselect_b64 s[0:1], -1, 0
	s_cmp_lt_i32 s3, s73
	s_cselect_b64 s[4:5], -1, 0
	s_and_b64 s[0:1], s[0:1], s[4:5]
	s_andn2_b64 vcc, exec, s[0:1]
	s_cbranch_vccnz .LBB0_899
	s_mov_b64 s[8:9], s[56:57]
	s_mov_b64 s[4:5], s[56:57]
	s_mov_b64 s[6:7], s[56:57]
	s_mov_b64 s[0:1], s[56:57]
	v_mov_b32_e32 v1, v0
	v_readlane_b32 s10, v252, 60
	v_mbcnt_lo_u32_b32 v1, -1, v1
	v_writelane_b32 v255, s71, 30
	v_mbcnt_hi_u32_b32 v1, -1, v1
	v_readlane_b32 s3, v252, 8
	v_readlane_b32 s11, v252, 61
	v_writelane_b32 v255, s36, 31
	v_add_u32_e32 v126, s3, v1
	v_cndmask_b32_e64 v1, 0, 1, s[10:11]
	v_writelane_b32 v255, s37, 32
	v_cmp_ne_u32_e64 s[12:13], 1, v1
	s_andn2_b64 vcc, exec, s[10:11]
	s_waitcnt vmcnt(0)
	v_ashrrev_i32_e32 v8, 6, v126
	v_writelane_b32 v255, s12, 33
	v_readfirstlane_b32 s3, v8
	s_nop 0
	v_writelane_b32 v255, s13, 34
	s_cbranch_vccnz .LBB0_658
	s_load_dwordx2 s[8:9], s[8:9], 0xf0
	v_readlane_b32 s10, v255, 30
	s_lshl_b32 s10, s10, 10
	v_and_b32_e32 v6, 31, v126
	v_writelane_b32 v255, s10, 35
	s_load_dwordx2 s[10:11], s[4:5], 0xf0
	s_nop 0
	s_load_dwordx2 s[4:5], s[6:7], 0xf0
	s_nop 0
	s_load_dwordx2 s[0:1], s[0:1], 0xf0
	s_waitcnt lgkmcnt(0)
	s_add_u32 s6, s8, 0x3fd00000
	s_addc_u32 s7, s9, 0
	v_writelane_b32 v255, s6, 36
	v_lshrrev_b32_e32 v2, 1, v126
	v_and_b32_e32 v128, 63, v126
	v_writelane_b32 v255, s7, 37
	s_add_u32 s6, s10, 0x58500000
	s_addc_u32 s7, s11, 0
	v_writelane_b32 v255, s6, 38
	s_add_u32 s0, s0, 0x6a500000
	v_and_b32_e32 v7, 16, v2
	v_writelane_b32 v255, s7, 39
	v_writelane_b32 v255, s0, 40
	s_addc_u32 s0, s1, 0
	s_movk_i32 s6, 0x240
	v_writelane_b32 v255, s0, 41
	s_cmp_gt_i32 s3, 3
	v_cmp_gt_i32_e64 s[6:7], s6, v126
	s_cselect_b64 s[0:1], -1, 0
	s_bfe_u32 s9, s3, 0x10001
	v_writelane_b32 v255, s6, 42
	s_movk_i32 s16, 0x90
	s_and_b32 s10, s3, 1
	v_writelane_b32 v255, s7, 43
	s_lshl_b32 s7, s9, 5
	v_or_b32_e32 v1, s7, v6
	v_mad_u32_u24 v131, v1, s16, v7
	v_bfe_u32 v1, v126, 2, 4
	v_lshlrev_b32_e32 v9, 2, v128
	s_lshl_b32 s6, s10, 5
	v_and_b32_e32 v2, 11, v1
	v_and_b32_e32 v3, 16, v126
	v_and_b32_e32 v4, 12, v9
	v_ashrrev_i32_e32 v127, 3, v126
	v_and_b32_e32 v5, 7, v126
	v_bfe_u32 v11, v126, 5, 1
	v_mul_u32_u24_e32 v2, 0x90, v2
	v_or3_b32 v10, v3, s7, v4
	v_or3_b32 v3, v3, s6, v4
	s_lshl_b32 s11, s9, 6
	v_and_b32_e32 v13, 8, v1
	v_or_b32_e32 v132, s6, v6
	v_lshl_add_u32 v134, v10, 1, v2
	v_lshl_add_u32 v135, v3, 1, v2
	v_or_b32_e32 v1, s11, v13
	v_lshlrev_b32_e32 v16, 5, v5
	v_readlane_b32 s8, v254, 51
	v_lshlrev_b32_e32 v2, 8, v127
	v_lshlrev_b32_e32 v10, 2, v11
	v_mad_u32_u24 v136, v132, s16, v1
	v_add_u32_e32 v1, s8, v9
	v_add3_u32 v137, s8, v16, v2
	v_readlane_b32 s8, v254, 52
	v_or_b32_e32 v12, s6, v10
	v_lshlrev_b32_e32 v3, 2, v126
	v_add_u32_e32 v139, s8, v9
	v_mul_lo_u32 v9, v127, s16
	s_ashr_i32 s14, s3, 1
	v_cmp_le_u32_e32 vcc, v6, v12
	v_lshlrev_b32_e32 v129, 3, v5
	v_add_u32_e32 v138, s8, v3
	v_readlane_b32 s8, v254, 53
	v_cmp_eq_u32_e64 s[12:13], 0, v5
	v_lshl_add_u32 v5, v5, 4, v9
	s_cmp_gt_i32 s14, 1
	v_cndmask_b32_e64 v9, 0, 1, vcc
	v_cmp_lt_u32_e32 vcc, v6, v12
	v_add_u32_e32 v140, s8, v16
	v_readlane_b32 s8, v254, 54
	v_writelane_b32 v255, s12, 44
	v_cndmask_b32_e64 v14, 0, 1, vcc
	s_cselect_b64 vcc, -1, 0
	v_add_u32_e32 v141, s8, v16
	v_readlane_b32 s8, v254, 55
	v_writelane_b32 v255, s13, 45
	s_and_b64 s[12:13], vcc, exec
	v_add_u32_e32 v142, s8, v16
	s_cselect_b32 s8, 0x2400, 0
	s_bitcmp0_b32 s3, 1
	s_movk_i32 s12, 0x4800
	s_cselect_b32 s15, s12, 0x6c00
	s_cmp_eq_u32 s14, 2
	s_mov_b32 s12, 0xfc00
	s_cselect_b32 s12, s12, 0x12000
	s_cmp_lg_u32 s14, 1
	s_cselect_b32 s14, s12, 0xd800
	s_cmp_lt_u32 s3, 2
	s_cselect_b64 s[40:41], -1, 0
	s_and_b64 s[12:13], s[40:41], exec
	v_readlane_b32 s17, v254, 56
	s_cselect_b32 s3, 0xb400, s14
	s_lshl_b32 s9, s9, 7
	s_add_i32 s3, s3, 0
	s_add_i32 s15, s15, 0
	s_add_i32 s9, s17, s9
	s_add_u32 s4, s4, s11
	v_cndmask_b32_e32 v17, v14, v9, vcc
	s_addc_u32 s5, s5, 0
	v_lshlrev_b32_e32 v14, 3, v11
	v_mov_b32_e32 v15, v0
	v_lshl_add_u64 v[14:15], s[4:5], 0, v[14:15]
	s_mov_b64 s[4:5], 0x62500000
	v_lshl_add_u64 v[96:97], v[14:15], 0, s[4:5]
	v_cmp_lt_i32_e64 s[4:5], 0, v8
	v_mad_u32_u24 v133, v132, s16, v7
	v_add_u32_e32 v149, s15, v7
	v_writelane_b32 v255, s4, 46
	v_lshl_or_b32 v7, s10, 6, v13
	v_or_b32_e32 v13, 1, v12
	v_writelane_b32 v255, s5, 47
	v_cmp_lt_i32_e64 s[4:5], 1, v8
	v_or_b32_e32 v14, 2, v12
	v_readlane_b32 s10, v254, 57
	v_writelane_b32 v255, s4, 48
	v_add_u32_e32 v148, s17, v16
	v_add_u32_e32 v151, s10, v16
	v_writelane_b32 v255, s5, 49
	v_cmp_lt_i32_e64 s[4:5], 2, v8
	v_lshlrev_b32_e32 v9, 4, v11
	v_and_b32_e32 v11, 1, v17
	v_writelane_b32 v255, s4, 50
	v_cmp_eq_u32_e64 s[62:63], 1, v11
	v_cndmask_b32_e32 v11, v12, v13, vcc
	v_writelane_b32 v255, s5, 51
	v_cmp_lt_i32_e64 s[4:5], 3, v8
	v_cmp_gt_u32_e64 s[64:65], v6, v11
	v_or_b32_e32 v10, s7, v10
	v_writelane_b32 v255, s4, 52
	v_add_u32_e32 v196, s10, v3
	v_readlane_b32 s10, v254, 63
	v_writelane_b32 v255, s5, 53
	v_cmp_lt_i32_e64 s[4:5], 4, v8
	v_add_u32_e32 v4, 0, v133
	v_lshlrev_b32_e32 v2, 11, v8
	v_writelane_b32 v255, s4, 54
	v_cmp_lt_i32_e64 s[60:61], 6, v8
	v_mad_u32_u24 v174, v6, s16, v7
	v_writelane_b32 v255, s5, 55
	v_cmp_lt_i32_e64 s[4:5], 5, v8
	v_mul_u32_u24_e32 v8, 0x90, v6
	v_lshl_add_u32 v198, v126, 4, s10
	v_writelane_b32 v255, s4, 56
	v_add_u32_e32 v193, s9, v9
	v_add_u32_e32 v194, s8, v4
	v_writelane_b32 v255, s5, 57
	v_readlane_b32 s4, v254, 58
	v_readlane_b32 s10, v255, 11
	v_readlane_b32 s11, v255, 12
	v_add_u32_e32 v152, s4, v16
	v_readlane_b32 s4, v254, 59
	v_sub_u32_e32 v130, 0x7ff, v127
	v_cmp_lt_i32_e64 s[44:45], 0, v127
	v_add_u32_e32 v153, s4, v16
	v_readlane_b32 s4, v254, 60
	v_cmp_eq_u32_e64 s[46:47], 63, v127
	v_add_u32_e32 v154, s4, v16
	v_readlane_b32 s4, v254, 61
	v_lshl_add_u32 v150, v132, 2, s17
	v_lshrrev_b32_e32 v157, 3, v127
	v_mul_u32_u24_e32 v157, 0x700, v157
	v_sub_u32_e32 v157, v137, v157
	v_add_u32_e32 v157, 0x4800, v157
	v_and_b32_e32 v143, 7, v127
	v_cmp_eq_u32_e64 s[100:101], 0, v143
	v_add_u32_e32 v143, 0xffffff00, v137
	s_nop 1
	v_cndmask_b32_e64 v143, v143, v157, s[100:101]
	v_add_u32_e32 v157, 16, v143
	v_add_u32_e32 v155, s4, v16
	v_readlane_b32 s4, v254, 62
	v_add_u32_e32 v197, 0xfffffe00, v126
	v_sub_u32_e32 v199, 0x7bf, v127
	v_add_u32_e32 v156, s4, v16
	v_cmp_eq_u32_e64 s[4:5], v12, v6
	v_add_u32_e32 v200, 0, v5
	v_add_u32_e32 v201, v149, v8
	v_cndmask_b32_e64 v158, 0, 1.0, s[4:5]
	v_cmp_eq_u32_e64 s[4:5], v13, v6
	v_add_u32_e32 v202, v1, v2
	s_mov_b32 s51, s10
	v_cndmask_b32_e64 v159, 0, 1.0, s[4:5]
	v_cmp_le_u32_e64 s[4:5], v6, v14
	s_nop 1
	v_cndmask_b32_e64 v15, 0, 1, s[4:5]
	v_cmp_lt_u32_e64 s[4:5], v6, v14
	s_nop 1
	v_cndmask_b32_e64 v16, 0, 1, s[4:5]
	v_cndmask_b32_e32 v15, v16, v15, vcc
	v_and_b32_e32 v15, 1, v15
	v_cmp_eq_u32_e64 s[66:67], 1, v15
	v_cmp_eq_u32_e64 s[4:5], v14, v6
	v_or_b32_e32 v15, 3, v12
	s_nop 0
	v_cndmask_b32_e64 v160, 0, 1.0, s[4:5]
	v_cmp_le_u32_e64 s[4:5], v6, v15
	s_nop 1
	v_cndmask_b32_e64 v16, 0, 1, s[4:5]
	v_cmp_lt_u32_e64 s[4:5], v6, v15
	s_nop 1
	v_cndmask_b32_e64 v17, 0, 1, s[4:5]
	v_cndmask_b32_e32 v16, v17, v16, vcc
	v_and_b32_e32 v16, 1, v16
	v_cmp_eq_u32_e64 s[68:69], 1, v16
	v_cmp_eq_u32_e64 s[4:5], v15, v6
	v_or_b32_e32 v16, 8, v12
	s_nop 0
	v_cndmask_b32_e64 v161, 0, 1.0, s[4:5]
	v_cmp_le_u32_e64 s[4:5], v6, v16
	s_nop 1
	v_cndmask_b32_e64 v17, 0, 1, s[4:5]
	v_cmp_lt_u32_e64 s[4:5], v6, v16
	s_nop 1
	v_cndmask_b32_e64 v18, 0, 1, s[4:5]
	v_cndmask_b32_e32 v17, v18, v17, vcc
	v_and_b32_e32 v17, 1, v17
	v_cmp_eq_u32_e64 s[70:71], 1, v17
	v_cmp_eq_u32_e64 s[4:5], v16, v6
	v_or_b32_e32 v17, 9, v12
	s_nop 0
	v_cndmask_b32_e64 v162, 0, 1.0, s[4:5]
	v_cmp_le_u32_e64 s[4:5], v6, v17
	s_nop 1
	v_cndmask_b32_e64 v18, 0, 1, s[4:5]
	v_cmp_lt_u32_e64 s[4:5], v6, v17
	s_nop 1
	v_cndmask_b32_e64 v19, 0, 1, s[4:5]
	v_cndmask_b32_e32 v18, v19, v18, vcc
	v_and_b32_e32 v18, 1, v18
	v_cmp_eq_u32_e64 s[72:73], 1, v18
	v_cmp_eq_u32_e64 s[4:5], v17, v6
	v_or_b32_e32 v18, 10, v12
	s_nop 0
	v_cndmask_b32_e64 v163, 0, 1.0, s[4:5]
	v_cmp_le_u32_e64 s[4:5], v6, v18
	s_nop 1
	v_cndmask_b32_e64 v19, 0, 1, s[4:5]
	v_cmp_lt_u32_e64 s[4:5], v6, v18
	s_nop 1
	v_cndmask_b32_e64 v20, 0, 1, s[4:5]
	v_cndmask_b32_e32 v19, v20, v19, vcc
	v_and_b32_e32 v19, 1, v19
	v_cmp_eq_u32_e64 s[74:75], 1, v19
	v_cmp_eq_u32_e64 s[4:5], v18, v6
	v_or_b32_e32 v19, 11, v12
	s_nop 0
	v_cndmask_b32_e64 v164, 0, 1.0, s[4:5]
	v_cmp_le_u32_e64 s[4:5], v6, v19
	s_nop 1
	v_cndmask_b32_e64 v20, 0, 1, s[4:5]
	v_cmp_lt_u32_e64 s[4:5], v6, v19
	s_nop 1
	v_cndmask_b32_e64 v21, 0, 1, s[4:5]
	v_cndmask_b32_e32 v20, v21, v20, vcc
	v_and_b32_e32 v20, 1, v20
	v_cmp_eq_u32_e64 s[76:77], 1, v20
	v_cmp_eq_u32_e64 s[4:5], v19, v6
	v_or_b32_e32 v20, 16, v12
	s_nop 0
	v_cndmask_b32_e64 v165, 0, 1.0, s[4:5]
	v_cmp_le_u32_e64 s[4:5], v6, v20
	s_nop 1
	v_cndmask_b32_e64 v21, 0, 1, s[4:5]
	v_cmp_lt_u32_e64 s[4:5], v6, v20
	s_nop 1
	v_cndmask_b32_e64 v22, 0, 1, s[4:5]
	v_cndmask_b32_e32 v21, v22, v21, vcc
	v_and_b32_e32 v21, 1, v21
	v_cmp_eq_u32_e64 s[78:79], 1, v21
	v_cmp_eq_u32_e64 s[4:5], v20, v6
	v_or_b32_e32 v21, 17, v12
	s_nop 0
	v_cndmask_b32_e64 v166, 0, 1.0, s[4:5]
	v_cmp_le_u32_e64 s[4:5], v6, v21
	s_nop 1
	v_cndmask_b32_e64 v22, 0, 1, s[4:5]
	v_cmp_lt_u32_e64 s[4:5], v6, v21
	s_nop 1
	v_cndmask_b32_e64 v23, 0, 1, s[4:5]
	v_cndmask_b32_e32 v22, v23, v22, vcc
	v_and_b32_e32 v22, 1, v22
	v_cmp_eq_u32_e64 s[80:81], 1, v22
	v_cmp_eq_u32_e64 s[4:5], v21, v6
	v_or_b32_e32 v22, 18, v12
	s_nop 0
	v_cndmask_b32_e64 v167, 0, 1.0, s[4:5]
	v_cmp_le_u32_e64 s[4:5], v6, v22
	s_nop 1
	v_cndmask_b32_e64 v23, 0, 1, s[4:5]
	v_cmp_lt_u32_e64 s[4:5], v6, v22
	s_nop 1
	v_cndmask_b32_e64 v24, 0, 1, s[4:5]
	v_cndmask_b32_e32 v23, v24, v23, vcc
	v_and_b32_e32 v23, 1, v23
	v_cmp_eq_u32_e64 s[82:83], 1, v23
	v_cmp_eq_u32_e64 s[4:5], v22, v6
	v_or_b32_e32 v23, 19, v12
	s_nop 0
	v_cndmask_b32_e64 v168, 0, 1.0, s[4:5]
	v_cmp_le_u32_e64 s[4:5], v6, v23
	s_nop 1
	v_cndmask_b32_e64 v24, 0, 1, s[4:5]
	v_cmp_lt_u32_e64 s[4:5], v6, v23
	s_nop 1
	v_cndmask_b32_e64 v25, 0, 1, s[4:5]
	v_cndmask_b32_e32 v24, v25, v24, vcc
	v_and_b32_e32 v24, 1, v24
	v_cmp_eq_u32_e64 s[84:85], 1, v24
	v_cmp_eq_u32_e64 s[4:5], v23, v6
	v_or_b32_e32 v24, 24, v12
	s_nop 0
	v_cndmask_b32_e64 v169, 0, 1.0, s[4:5]
	v_cmp_le_u32_e64 s[4:5], v6, v24
	s_nop 1
	v_cndmask_b32_e64 v25, 0, 1, s[4:5]
	v_cmp_lt_u32_e64 s[4:5], v6, v24
	s_nop 1
	v_cndmask_b32_e64 v26, 0, 1, s[4:5]
	v_cndmask_b32_e32 v25, v26, v25, vcc
	v_and_b32_e32 v25, 1, v25
	v_cmp_eq_u32_e64 s[86:87], 1, v25
	v_cmp_eq_u32_e64 s[4:5], v24, v6
	v_or_b32_e32 v25, 25, v12
	s_nop 0
	v_cndmask_b32_e64 v170, 0, 1.0, s[4:5]
	v_cmp_le_u32_e64 s[4:5], v6, v25
	s_nop 1
	v_cndmask_b32_e64 v26, 0, 1, s[4:5]
	v_cmp_lt_u32_e64 s[4:5], v6, v25
	s_nop 1
	v_cndmask_b32_e64 v27, 0, 1, s[4:5]
	v_cndmask_b32_e32 v26, v27, v26, vcc
	v_and_b32_e32 v26, 1, v26
	v_cmp_eq_u32_e64 s[88:89], 1, v26
	v_cmp_eq_u32_e64 s[4:5], v25, v6
	v_or_b32_e32 v26, 26, v12
	s_nop 0
	v_cndmask_b32_e64 v171, 0, 1.0, s[4:5]
	v_cmp_le_u32_e64 s[4:5], v6, v26
	s_nop 1
	v_cndmask_b32_e64 v27, 0, 1, s[4:5]
	v_cmp_lt_u32_e64 s[4:5], v6, v26
	s_nop 1
	v_cndmask_b32_e64 v28, 0, 1, s[4:5]
	v_cndmask_b32_e32 v27, v28, v27, vcc
	v_and_b32_e32 v27, 1, v27
	v_cmp_eq_u32_e64 s[90:91], 1, v27
	v_cmp_eq_u32_e64 s[4:5], v26, v6
	v_or_b32_e32 v27, 27, v12
	s_nop 0
	v_cndmask_b32_e64 v172, 0, 1.0, s[4:5]
	v_cmp_le_u32_e64 s[4:5], v6, v27
	s_nop 1
	v_cndmask_b32_e64 v28, 0, 1, s[4:5]
	v_cmp_lt_u32_e64 s[4:5], v6, v27
	s_nop 1
	v_cndmask_b32_e64 v29, 0, 1, s[4:5]
	v_cndmask_b32_e32 v28, v29, v28, vcc
	v_and_b32_e32 v28, 1, v28
	v_cmp_eq_u32_e64 s[92:93], 1, v28
	v_cmp_eq_u32_e64 s[4:5], v27, v6
	v_or_b32_e32 v28, 32, v6
	v_mov_b32_e32 v29, 0x1200
	v_cndmask_b32_e64 v173, 0, 1.0, s[4:5]
	v_cmp_le_u32_e64 s[4:5], v28, v12
	v_mad_u32_u24 v175, v6, s16, v29
	v_cmp_gt_u32_e64 s[96:97], v28, v11
	v_cndmask_b32_e64 v29, 0, 1, s[4:5]
	v_cmp_lt_u32_e64 s[4:5], v28, v12
	v_add_u32_e32 v195, v7, v175
	s_nop 0
	v_cndmask_b32_e64 v30, 0, 1, s[4:5]
	v_cmp_eq_u32_e64 s[4:5], v12, v28
	v_cndmask_b32_e32 v29, v30, v29, vcc
	v_and_b32_e32 v29, 1, v29
	v_cndmask_b32_e64 v176, 0, 1.0, s[4:5]
	v_cmp_eq_u32_e64 s[4:5], v13, v28
	v_cmp_eq_u32_e64 s[94:95], 1, v29
	s_nop 0
	v_cndmask_b32_e64 v177, 0, 1.0, s[4:5]
	v_cmp_le_u32_e64 s[4:5], v28, v14
	s_nop 1
	v_cndmask_b32_e64 v12, 0, 1, s[4:5]
	v_cmp_lt_u32_e64 s[4:5], v28, v14
	s_nop 1
	v_cndmask_b32_e64 v13, 0, 1, s[4:5]
	v_cmp_eq_u32_e64 s[4:5], v14, v28
	v_cndmask_b32_e32 v11, v13, v12, vcc
	v_and_b32_e32 v11, 1, v11
	v_cndmask_b32_e64 v178, 0, 1.0, s[4:5]
	v_cmp_le_u32_e64 s[4:5], v28, v15
	s_nop 1
	v_cndmask_b32_e64 v14, 0, 1, s[4:5]
	v_cmp_lt_u32_e64 s[4:5], v28, v15
	s_nop 1
	v_cndmask_b32_e64 v29, 0, 1, s[4:5]
	v_cmp_eq_u32_e64 s[4:5], v15, v28
	v_cndmask_b32_e32 v12, v29, v14, vcc
	s_nop 0
	v_cndmask_b32_e64 v179, 0, 1.0, s[4:5]
	v_cmp_le_u32_e64 s[4:5], v28, v16
	s_nop 1
	v_cndmask_b32_e64 v15, 0, 1, s[4:5]
	v_cmp_lt_u32_e64 s[4:5], v28, v16
	s_nop 1
	v_cndmask_b32_e64 v30, 0, 1, s[4:5]
	v_cmp_eq_u32_e64 s[4:5], v16, v28
	v_cndmask_b32_e32 v13, v30, v15, vcc
	s_nop 0
	v_cndmask_b32_e64 v180, 0, 1.0, s[4:5]
	v_cmp_le_u32_e64 s[4:5], v28, v17
	s_nop 1
	v_cndmask_b32_e64 v16, 0, 1, s[4:5]
	v_cmp_lt_u32_e64 s[4:5], v28, v17
	s_nop 1
	v_cndmask_b32_e64 v31, 0, 1, s[4:5]
	v_cmp_eq_u32_e64 s[4:5], v17, v28
	v_cndmask_b32_e32 v14, v31, v16, vcc
	v_and_b32_e32 v4, 1, v14
	v_cndmask_b32_e64 v181, 0, 1.0, s[4:5]
	v_cmp_le_u32_e64 s[4:5], v28, v18
	v_cmp_eq_u32_e64 s[10:11], 1, v4
	s_nop 0
	v_cndmask_b32_e64 v17, 0, 1, s[4:5]
	v_cmp_lt_u32_e64 s[4:5], v28, v18
	s_nop 1
	v_cndmask_b32_e64 v32, 0, 1, s[4:5]
	v_cmp_eq_u32_e64 s[4:5], v18, v28
	v_cndmask_b32_e32 v15, v32, v17, vcc
	s_nop 0
	v_cndmask_b32_e64 v182, 0, 1.0, s[4:5]
	v_cmp_le_u32_e64 s[4:5], v28, v19
	s_nop 1
	v_cndmask_b32_e64 v18, 0, 1, s[4:5]
	v_cmp_lt_u32_e64 s[4:5], v28, v19
	s_nop 1
	v_cndmask_b32_e64 v33, 0, 1, s[4:5]
	v_cmp_eq_u32_e64 s[4:5], v19, v28
	v_cndmask_b32_e32 v16, v33, v18, vcc
	v_and_b32_e32 v9, 1, v16
	v_cndmask_b32_e64 v183, 0, 1.0, s[4:5]
	v_cmp_le_u32_e64 s[4:5], v28, v20
	v_cmp_eq_u32_e64 s[14:15], 1, v9
	s_nop 0
	v_cndmask_b32_e64 v19, 0, 1, s[4:5]
	v_cmp_lt_u32_e64 s[4:5], v28, v20
	s_nop 1
	v_cndmask_b32_e64 v34, 0, 1, s[4:5]
	v_cmp_eq_u32_e64 s[4:5], v20, v28
	v_cndmask_b32_e32 v17, v34, v19, vcc
	s_nop 0
	v_cndmask_b32_e64 v184, 0, 1.0, s[4:5]
	v_cmp_le_u32_e64 s[4:5], v28, v21
	s_nop 1
	v_cndmask_b32_e64 v20, 0, 1, s[4:5]
	v_cmp_lt_u32_e64 s[4:5], v28, v21
	s_nop 1
	v_cndmask_b32_e64 v35, 0, 1, s[4:5]
	v_cmp_eq_u32_e64 s[4:5], v21, v28
	v_cndmask_b32_e32 v18, v35, v20, vcc
	s_nop 0
	v_cndmask_b32_e64 v185, 0, 1.0, s[4:5]
	v_cmp_le_u32_e64 s[4:5], v28, v22
	s_nop 1
	v_cndmask_b32_e64 v21, 0, 1, s[4:5]
	v_cmp_lt_u32_e64 s[4:5], v28, v22
	s_nop 1
	v_cndmask_b32_e64 v36, 0, 1, s[4:5]
	v_cmp_eq_u32_e64 s[4:5], v22, v28
	v_cndmask_b32_e32 v19, v36, v21, vcc
	s_nop 0
	v_cndmask_b32_e64 v186, 0, 1.0, s[4:5]
	v_cmp_le_u32_e64 s[4:5], v28, v23
	s_nop 1
	v_cndmask_b32_e64 v22, 0, 1, s[4:5]
	v_cmp_lt_u32_e64 s[4:5], v28, v23
	s_nop 1
	v_cndmask_b32_e64 v37, 0, 1, s[4:5]
	v_cmp_eq_u32_e64 s[4:5], v23, v28
	v_cndmask_b32_e32 v20, v37, v22, vcc
	s_nop 0
	v_cndmask_b32_e64 v187, 0, 1.0, s[4:5]
	v_cmp_le_u32_e64 s[4:5], v28, v24
	s_nop 1
	v_cndmask_b32_e64 v23, 0, 1, s[4:5]
	v_cmp_lt_u32_e64 s[4:5], v28, v24
	s_nop 1
	v_cndmask_b32_e64 v38, 0, 1, s[4:5]
	v_cmp_eq_u32_e64 s[4:5], v24, v28
	v_cndmask_b32_e32 v21, v38, v23, vcc
	v_and_b32_e32 v14, 1, v21
	v_cndmask_b32_e64 v188, 0, 1.0, s[4:5]
	v_cmp_le_u32_e64 s[4:5], v28, v25
	v_cmp_eq_u32_e64 s[24:25], 1, v14
	s_nop 0
	v_cndmask_b32_e64 v24, 0, 1, s[4:5]
	v_cmp_lt_u32_e64 s[4:5], v28, v25
	s_nop 1
	v_cndmask_b32_e64 v39, 0, 1, s[4:5]
	v_cmp_eq_u32_e64 s[4:5], v25, v28
	v_cndmask_b32_e32 v22, v39, v24, vcc
	s_nop 0
	v_cndmask_b32_e64 v189, 0, 1.0, s[4:5]
	v_cmp_le_u32_e64 s[4:5], v28, v26
	s_nop 1
	v_cndmask_b32_e64 v25, 0, 1, s[4:5]
	v_cmp_lt_u32_e64 s[4:5], v28, v26
	s_nop 1
	v_cndmask_b32_e64 v40, 0, 1, s[4:5]
	v_cmp_eq_u32_e64 s[4:5], v26, v28
	v_cndmask_b32_e32 v23, v40, v25, vcc
	v_or_b32_e32 v25, 1, v10
	v_cndmask_b32_e64 v190, 0, 1.0, s[4:5]
	v_cmp_le_u32_e64 s[4:5], v28, v27
	v_and_b32_e32 v16, 1, v23
	v_cmp_eq_u32_e64 s[28:29], 1, v16
	v_cndmask_b32_e64 v26, 0, 1, s[4:5]
	v_cmp_lt_u32_e64 s[4:5], v28, v27
	s_nop 1
	v_cndmask_b32_e64 v41, 0, 1, s[4:5]
	v_cndmask_b32_e32 v24, v41, v26, vcc
	v_cmp_eq_u32_e32 vcc, v27, v28
	v_or_b32_e32 v26, 2, v10
	v_cmp_eq_u32_e64 s[4:5], 1, v11
	v_cndmask_b32_e64 v191, 0, 1.0, vcc
	v_cmp_eq_u32_e32 vcc, v10, v132
	v_mov_b32_e32 v11, 0x7ff
	v_bitop3_b32 v192, s6, v11, v6 bitop3:0x36
	v_cndmask_b32_e64 v98, 0, 1.0, vcc
	v_cmp_eq_u32_e32 vcc, v25, v132
	v_or_b32_e32 v25, 3, v10
	v_and_b32_e32 v6, 1, v13
	v_cndmask_b32_e64 v99, 0, 1.0, vcc
	v_cmp_eq_u32_e32 vcc, v25, v132
	v_or_b32_e32 v25, 9, v10
	v_cmp_eq_u32_e64 s[8:9], 1, v6
	v_cndmask_b32_e64 v101, 0, 1.0, vcc
	v_cmp_eq_u32_e32 vcc, v26, v132
	v_or_b32_e32 v26, 8, v10
	v_and_b32_e32 v6, 1, v15
	v_cndmask_b32_e64 v100, 0, 1.0, vcc
	v_cmp_eq_u32_e32 vcc, v25, v132
	v_or_b32_e32 v25, 11, v10
	v_and_b32_e32 v11, 1, v18
	v_cndmask_b32_e64 v103, 0, 1.0, vcc
	v_cmp_eq_u32_e32 vcc, v26, v132
	v_or_b32_e32 v26, 10, v10
	v_and_b32_e32 v13, 1, v20
	v_cndmask_b32_e64 v102, 0, 1.0, vcc
	v_cmp_eq_u32_e32 vcc, v25, v132
	v_or_b32_e32 v25, 17, v10
	v_and_b32_e32 v15, 1, v22
	v_cndmask_b32_e64 v105, 0, 1.0, vcc
	v_cmp_eq_u32_e32 vcc, v26, v132
	v_or_b32_e32 v26, 16, v10
	v_cmp_eq_u32_e64 s[12:13], 1, v6
	v_cndmask_b32_e64 v104, 0, 1.0, vcc
	v_cmp_eq_u32_e32 vcc, v25, v132
	v_or_b32_e32 v25, 19, v10
	v_cmp_eq_u32_e64 s[18:19], 1, v11
	v_cndmask_b32_e64 v107, 0, 1.0, vcc
	v_cmp_eq_u32_e32 vcc, v26, v132
	v_or_b32_e32 v26, 18, v10
	v_cmp_eq_u32_e64 s[22:23], 1, v13
	v_cndmask_b32_e64 v106, 0, 1.0, vcc
	v_cmp_eq_u32_e32 vcc, v25, v132
	v_or_b32_e32 v25, 25, v10
	v_cmp_eq_u32_e64 s[26:27], 1, v15
	v_cndmask_b32_e64 v109, 0, 1.0, vcc
	v_cmp_eq_u32_e32 vcc, v26, v132
	v_or_b32_e32 v26, 24, v10
	s_nop 0
	v_cndmask_b32_e64 v108, 0, 1.0, vcc
	v_cmp_eq_u32_e32 vcc, v25, v132
	v_or_b32_e32 v25, 27, v10
	v_or_b32_e32 v10, 26, v10
	v_cndmask_b32_e64 v111, 0, 1.0, vcc
	v_cmp_eq_u32_e32 vcc, v26, v132
	s_nop 1
	v_cndmask_b32_e64 v110, 0, 1.0, vcc
	v_cmp_eq_u32_e32 vcc, v25, v132
	s_nop 1
	v_cndmask_b32_e64 v113, 0, 1.0, vcc
	v_cmp_eq_u32_e32 vcc, v10, v132
	v_and_b32_e32 v10, 1, v12
	v_cmp_eq_u32_e64 s[6:7], 1, v10
	v_and_b32_e32 v10, 1, v17
	v_and_b32_e32 v12, 1, v19
	v_and_b32_e32 v17, 1, v24
	v_cndmask_b32_e64 v112, 0, 1.0, vcc
	v_cmp_eq_u32_e64 s[16:17], 1, v10
	v_cmp_eq_u32_e64 s[20:21], 1, v12
	v_cmp_eq_u32_e64 s[30:31], 1, v17
	s_branch .LBB0_526

.LBB0_561:
	v_mov_b32_e32 v206, v133
	v_mov_b32_e32 v208, v135
	v_mov_b32_e32 v207, v131
	v_mov_b32_e32 v209, v134
	v_mov_b32_e32 v205, v136
	s_waitcnt vmcnt(1)
	v_lshlrev_b32_e32 v20, 16, v88
	v_and_b32_e32 v21, 0xffff0000, v88
	v_lshlrev_b32_e32 v22, 16, v89
	v_and_b32_e32 v23, 0xffff0000, v89
	v_lshlrev_b32_e32 v24, 16, v90
	v_and_b32_e32 v25, 0xffff0000, v90
	v_lshlrev_b32_e32 v26, 16, v91
	v_and_b32_e32 v27, 0xffff0000, v91
	ds_write_b128 v137, v[20:23]
	ds_write_b128 v137, v[24:27] offset:16
	s_waitcnt lgkmcnt(0)
	ds_read2st64_b32 v[20:21], v202 offset1:1
	ds_read2st64_b32 v[22:23], v202 offset0:2 offset1:3
	ds_read2st64_b32 v[26:27], v202 offset0:4 offset1:5
	ds_read2st64_b32 v[28:29], v202 offset0:6 offset1:7
	v_mov_b32_e32 v3, 0
	s_waitcnt lgkmcnt(3)
	v_add_f32_e32 v24, 0, v20
	v_add_f32_e32 v25, v24, v21
	s_waitcnt lgkmcnt(2)
	v_add_f32_e32 v22, v25, v22
	v_add_f32_e32 v23, v22, v23
	s_waitcnt lgkmcnt(1)
	v_add_f32_e32 v20, v23, v26
	v_add_f32_e32 v21, v20, v27
	s_waitcnt lgkmcnt(0)
	v_add_f32_e32 v1, v21, v28
	v_add_f32_e32 v2, v1, v29
	v_mov_b32_e32 v26, 0
	ds_write_b32 v138, v2
	s_waitcnt lgkmcnt(0)
	s_barrier
	s_mov_b64 s[36:37], exec
	v_readlane_b32 s38, v255, 46
	v_readlane_b32 s39, v255, 47
	s_and_b64 s[38:39], s[36:37], s[38:39]
	s_mov_b64 exec, s[38:39]
	s_cbranch_execz .LBB0_563
	ds_read_b32 v26, v139
	s_waitcnt lgkmcnt(0)
	v_add_f32_e32 v26, 0, v26
.LBB0_563:
	s_or_b64 exec, exec, s[36:37]
	s_mov_b64 s[36:37], exec
	v_readlane_b32 s38, v255, 48
	v_readlane_b32 s39, v255, 49
	s_and_b64 s[38:39], s[36:37], s[38:39]
	s_mov_b64 exec, s[38:39]
	ds_read_b32 v3, v139 offset:256
	s_or_b64 exec, exec, s[36:37]
	v_mov_b32_e32 v27, 0
	v_mov_b32_e32 v28, 0
	s_mov_b64 s[36:37], exec
	v_readlane_b32 s38, v255, 50
	v_readlane_b32 s39, v255, 51
	s_and_b64 s[38:39], s[36:37], s[38:39]
	s_mov_b64 exec, s[38:39]
	ds_read_b32 v28, v139 offset:512
	s_or_b64 exec, exec, s[36:37]
	s_mov_b64 s[36:37], exec
	v_readlane_b32 s38, v255, 52
	v_readlane_b32 s39, v255, 53
	s_and_b64 s[38:39], s[36:37], s[38:39]
	s_mov_b64 exec, s[38:39]
	ds_read_b32 v27, v139 offset:768
	s_or_b64 exec, exec, s[36:37]
	v_mov_b32_e32 v29, 0
	v_mov_b32_e32 v30, 0
	s_mov_b64 s[36:37], exec
	v_readlane_b32 s38, v255, 54
	v_readlane_b32 s39, v255, 55
	s_and_b64 s[38:39], s[36:37], s[38:39]
	s_mov_b64 exec, s[38:39]
	ds_read_b32 v30, v139 offset:1024
	s_or_b64 exec, exec, s[36:37]
	s_mov_b64 s[36:37], exec
	v_readlane_b32 s38, v255, 56
	v_readlane_b32 s39, v255, 57
	s_and_b64 s[38:39], s[36:37], s[38:39]
	s_mov_b64 exec, s[38:39]
	ds_read_b32 v29, v139 offset:1280
	s_or_b64 exec, exec, s[36:37]
	v_mov_b32_e32 v31, 0
	s_and_saveexec_b64 s[36:37], s[60:61]
	ds_read_b32 v31, v139 offset:1536
	s_or_b64 exec, exec, s[36:37]
	s_waitcnt lgkmcnt(0)
	v_add_f32_e32 v3, v26, v3
	v_add_f32_e32 v3, v3, v28
	v_add_f32_e32 v3, v3, v27
	v_add_f32_e32 v3, v3, v30
	v_add_f32_e32 v3, v3, v29
	v_add_f32_e32 v3, v3, v31
	v_sub_u32_e32 v26, v202, v139
	v_add_u32_e32 v26, 0x4000, v26
	v_lshrrev_b32_e32 v26, 3, v26
	v_add_u32_e32 v26, v26, v139
	ds_write_b32 v26, v3 offset:2048
	v_add_f32_e32 v24, v24, v3
	v_add_f32_e32 v25, v25, v3
	v_add_f32_e32 v22, v22, v3
	v_add_f32_e32 v23, v23, v3
	v_add_f32_e32 v20, v20, v3
	v_add_f32_e32 v21, v21, v3
	v_add_f32_e32 v1, v1, v3
	v_add_f32_e32 v2, v2, v3
	ds_write2st64_b32 v202, v24, v25 offset1:1
	ds_write2st64_b32 v202, v22, v23 offset0:2 offset1:3
	ds_write2st64_b32 v202, v20, v21 offset0:4 offset1:5
	ds_write2st64_b32 v202, v1, v2 offset0:6 offset1:7
	s_waitcnt lgkmcnt(0)
	ds_read_b128 v[20:23], v151
	ds_read_b128 v[24:27], v151 offset:16
	ds_read_b128 v[28:31], v152
	ds_read_b128 v[32:35], v152 offset:16
	v_lshlrev_b32_e32 v2, 16, v52
	v_and_b32_e32 v3, 0xffff0000, v52
	v_lshlrev_b32_e32 v36, 16, v53
	v_and_b32_e32 v37, 0xffff0000, v53
	v_lshlrev_b32_e32 v1, 16, v60
	v_and_b32_e32 v40, 0xffff0000, v60
	v_lshlrev_b32_e32 v38, 16, v61
	v_and_b32_e32 v39, 0xffff0000, v61
	v_lshlrev_b32_e32 v42, 16, v56
	v_and_b32_e32 v43, 0xffff0000, v56
	v_lshlrev_b32_e32 v44, 16, v57
	v_and_b32_e32 v45, 0xffff0000, v57
	v_sub_f32_e32 v39, v39, v37
	v_sub_f32_e32 v38, v38, v36
	v_sub_f32_e32 v41, v40, v3
	v_sub_f32_e32 v40, v1, v2
	s_waitcnt lgkmcnt(3)
	v_pk_fma_f32 v[20:21], v[40:41], v[20:21], v[2:3]
	v_pk_fma_f32 v[22:23], v[38:39], v[22:23], v[36:37]
	v_sub_f32_e32 v3, v43, v3
	v_sub_f32_e32 v2, v42, v2
	v_sub_f32_e32 v37, v45, v37
	v_sub_f32_e32 v36, v44, v36
	s_waitcnt lgkmcnt(1)
	v_pk_fma_f32 v[120:121], v[36:37], v[30:31], v[22:23]
	v_pk_fma_f32 v[122:123], v[2:3], v[28:29], v[20:21]
	v_lshlrev_b32_e32 v2, 16, v54
	v_and_b32_e32 v3, 0xffff0000, v54
	v_lshlrev_b32_e32 v20, 16, v55
	v_and_b32_e32 v21, 0xffff0000, v55
	v_lshlrev_b32_e32 v1, 16, v62
	v_and_b32_e32 v28, 0xffff0000, v62
	v_lshlrev_b32_e32 v22, 16, v63
	v_and_b32_e32 v23, 0xffff0000, v63
	v_lshlrev_b32_e32 v30, 16, v58
	v_and_b32_e32 v31, 0xffff0000, v58
	v_lshlrev_b32_e32 v36, 16, v59
	v_and_b32_e32 v37, 0xffff0000, v59
	v_sub_f32_e32 v23, v23, v21
	v_sub_f32_e32 v22, v22, v20
	v_sub_f32_e32 v29, v28, v3
	v_sub_f32_e32 v28, v1, v2
	v_pk_fma_f32 v[24:25], v[28:29], v[24:25], v[2:3]
	v_pk_fma_f32 v[22:23], v[22:23], v[26:27], v[20:21]
	v_sub_f32_e32 v27, v31, v3
	v_sub_f32_e32 v26, v30, v2
	v_sub_f32_e32 v3, v37, v21
	v_sub_f32_e32 v2, v36, v20
	s_waitcnt lgkmcnt(0)
	v_pk_fma_f32 v[2:3], v[2:3], v[34:35], v[22:23]
	v_pk_fma_f32 v[124:125], v[26:27], v[32:33], v[24:25]
	ds_read_b128 v[20:23], v153
	ds_read_b128 v[24:27], v153 offset:16
	ds_read_b128 v[28:31], v154
	ds_read_b128 v[32:35], v154 offset:16
	v_lshlrev_b32_e32 v36, 16, v64
	v_and_b32_e32 v37, 0xffff0000, v64
	v_lshlrev_b32_e32 v38, 16, v65
	v_and_b32_e32 v39, 0xffff0000, v65
	v_lshlrev_b32_e32 v1, 16, v68
	v_and_b32_e32 v42, 0xffff0000, v68
	v_lshlrev_b32_e32 v40, 16, v69
	v_and_b32_e32 v41, 0xffff0000, v69
	v_lshlrev_b32_e32 v44, 16, v72
	v_and_b32_e32 v45, 0xffff0000, v72
	v_lshlrev_b32_e32 v46, 16, v73
	v_and_b32_e32 v47, 0xffff0000, v73
	v_sub_f32_e32 v41, v41, v39
	v_sub_f32_e32 v40, v40, v38
	v_sub_f32_e32 v43, v42, v37
	v_sub_f32_e32 v42, v1, v36
	s_waitcnt lgkmcnt(3)
	v_pk_fma_f32 v[20:21], v[42:43], v[20:21], v[36:37]
	v_pk_fma_f32 v[22:23], v[40:41], v[22:23], v[38:39]
	v_sub_f32_e32 v37, v45, v37
	v_sub_f32_e32 v36, v44, v36
	v_sub_f32_e32 v39, v47, v39
	v_sub_f32_e32 v38, v46, v38
	s_waitcnt lgkmcnt(1)
	v_pk_fma_f32 v[246:247], v[38:39], v[30:31], v[22:23]
	v_pk_fma_f32 v[232:233], v[36:37], v[28:29], v[20:21]
	v_lshlrev_b32_e32 v20, 16, v66
	v_and_b32_e32 v21, 0xffff0000, v66
	v_lshlrev_b32_e32 v22, 16, v67
	v_and_b32_e32 v23, 0xffff0000, v67
	v_lshlrev_b32_e32 v1, 16, v70
	v_and_b32_e32 v30, 0xffff0000, v70
	v_lshlrev_b32_e32 v28, 16, v71
	v_and_b32_e32 v29, 0xffff0000, v71
	v_lshlrev_b32_e32 v36, 16, v74
	v_and_b32_e32 v37, 0xffff0000, v74
	v_lshlrev_b32_e32 v38, 16, v75
	v_and_b32_e32 v39, 0xffff0000, v75
	v_sub_f32_e32 v29, v29, v23
	v_sub_f32_e32 v28, v28, v22
	v_sub_f32_e32 v31, v30, v21
	v_sub_f32_e32 v30, v1, v20
	v_pk_fma_f32 v[24:25], v[30:31], v[24:25], v[20:21]
	v_pk_fma_f32 v[26:27], v[28:29], v[26:27], v[22:23]
	v_sub_f32_e32 v21, v37, v21
	v_sub_f32_e32 v20, v36, v20
	v_sub_f32_e32 v23, v39, v23
	v_sub_f32_e32 v22, v38, v22
	s_waitcnt lgkmcnt(0)
	v_pk_fma_f32 v[248:249], v[22:23], v[34:35], v[26:27]
	v_pk_fma_f32 v[250:251], v[20:21], v[32:33], v[24:25]
	ds_read_b128 v[28:31], v155
	ds_read_b128 v[32:35], v155 offset:16
	ds_read_b128 v[24:27], v156
	ds_read_b128 v[20:23], v156 offset:16
	s_waitcnt vmcnt(0)
	v_lshlrev_b32_e32 v227, 16, v92
	ds_read_b128 v[36:39], v140
	ds_read_b128 v[40:43], v140 offset:16
	ds_read_b128 v[44:47], v141
	ds_read_b128 v[48:51], v141 offset:16
	ds_read_b128 v[228:231], v142
	ds_read_b128 v[242:245], v142 offset:16
	v_and_b32_e32 v226, 0xffff0000, v92
	s_waitcnt lgkmcnt(5)
	v_mul_f32_e32 v241, v232, v36
	v_add_f32_e32 v36, -1.0, v227
	v_lshlrev_b32_e32 v214, 16, v93
	s_waitcnt lgkmcnt(3)
	v_fma_f32 v36, v36, v44, 1.0
	v_add_f32_e32 v44, -1.0, v226
	v_mul_f32_e32 v237, v232, v36
	v_fma_f32 v44, v44, v45, 1.0
	v_mul_f32_e32 v240, v246, v38
	v_add_f32_e32 v38, -1.0, v214
	v_mul_f32_e32 v36, v122, v237
	v_mul_f32_e32 v235, v233, v44
	v_fma_f32 v38, v38, v46, 1.0
	s_waitcnt lgkmcnt(1)
	v_fma_f32 v36, v228, v36, 0
	v_mul_f32_e32 v239, v233, v37
	v_mul_f32_e32 v44, v123, v235
	v_mul_f32_e32 v233, v246, v38
	v_and_b32_e32 v213, 0xffff0000, v93
	v_fmac_f32_e32 v36, v229, v44
	v_mul_f32_e32 v38, v120, v233
	v_fmac_f32_e32 v36, v230, v38
	v_add_f32_e32 v38, -1.0, v213
	v_fma_f32 v38, v38, v47, 1.0
	v_mul_f32_e32 v230, v247, v38
	v_lshlrev_b32_e32 v212, 16, v94
	v_mul_f32_e32 v38, v121, v230
	v_fmac_f32_e32 v36, v231, v38
	v_add_f32_e32 v38, -1.0, v212
	v_fma_f32 v38, v38, v48, 1.0
	v_mul_f32_e32 v229, v250, v38
	v_and_b32_e32 v211, 0xffff0000, v94
	v_mul_f32_e32 v38, v124, v229
	s_waitcnt lgkmcnt(0)
	v_fmac_f32_e32 v36, v242, v38
	v_add_f32_e32 v38, -1.0, v211
	v_fma_f32 v38, v38, v49, 1.0
	v_mul_f32_e32 v228, v251, v38
	v_lshlrev_b32_e32 v210, 16, v95
	v_mul_f32_e32 v38, v125, v228
	v_fmac_f32_e32 v36, v243, v38
	v_add_f32_e32 v38, -1.0, v210
	v_mul_f32_e32 v37, v239, v239
	v_fma_f32 v38, v38, v50, 1.0
	v_fmac_f32_e32 v37, v241, v241
	v_mul_f32_e32 v232, v248, v38
	v_and_b32_e32 v1, 0xffff0000, v95
	v_fmac_f32_e32 v37, v240, v240
	v_mul_f32_e32 v238, v247, v39
	v_mul_f32_e32 v38, v2, v232
	v_fmac_f32_e32 v37, v238, v238
	v_mul_f32_e32 v236, v250, v40
	v_fmac_f32_e32 v36, v244, v38
	v_add_f32_e32 v38, -1.0, v1
	v_fmac_f32_e32 v37, v236, v236
	v_mul_f32_e32 v234, v251, v41
	v_fma_f32 v38, v38, v51, 1.0
	v_fmac_f32_e32 v37, v234, v234
	v_mul_f32_e32 v231, v248, v42
	v_mul_f32_e32 v225, v249, v38
	v_fmac_f32_e32 v37, v231, v231
	v_mul_f32_e32 v215, v249, v43
	v_mul_f32_e32 v38, v3, v225
	v_fmac_f32_e32 v37, v215, v215
	v_fmac_f32_e32 v36, v245, v38
	s_nop 0
	v_add_f32_dpp v37, v37, v37 quad_perm:[1,0,3,2] row_mask:0xf bank_mask:0xf bound_ctrl:1
	v_add_f32_dpp v36, v36, v36 quad_perm:[1,0,3,2] row_mask:0xf bank_mask:0xf bound_ctrl:1
	s_nop 0
	v_add_f32_dpp v242, v37, v37 quad_perm:[2,3,0,1] row_mask:0xf bank_mask:0xf bound_ctrl:1
	v_add_f32_dpp v36, v36, v36 quad_perm:[2,3,0,1] row_mask:0xf bank_mask:0xf bound_ctrl:1
	s_nop 0
	v_mov_b32_dpp v243, v242 row_half_mirror row_mask:0xf bank_mask:0xf bound_ctrl:1
	v_mov_b32_dpp v37, v36 row_half_mirror row_mask:0xf bank_mask:0xf bound_ctrl:1
	s_mov_b64 s[36:37], exec
	v_readlane_b32 s38, v255, 44
	v_readlane_b32 s39, v255, 45
	s_and_b64 s[38:39], s[36:37], s[38:39]
	s_mov_b64 exec, s[38:39]
	s_cbranch_execz .LBB0_577
	v_add_u32_e32 v38, s49, v127
	v_add_u32_e32 v39, 64, v204
	v_cndmask_b32_e64 v38, v39, v38, s[34:35]
	v_add_u32_e32 v38, s48, v38
	v_readlane_b32 s38, v255, 31
	v_ashrrev_i32_e32 v39, 31, v38
	v_readlane_b32 s39, v255, 32
	v_add_f32_e32 v36, v36, v37
	s_nop 0
	v_lshl_add_u64 v[38:39], v[38:39], 0, s[38:39]
	v_lshlrev_b64 v[38:39], 6, v[38:39]
	v_lshl_add_u64 v[38:39], s[54:55], 0, v[38:39]
	global_store_dword v[38:39], v36, off
